# third decode wave beside the recurrence (wave 7 awake), recurrence at prio 2
# baseline (speedup 1.0000x reference)
; __device__ __forceinline__ void scan_prompt_wave(const Params& P, unsigned char* lds, int b, int h, int quarter) {
;     ...
;         asm volatile("s_waitcnt vmcnt(0)" ::: "memory");
;         if (lane == 0) scw[0] = (unsigned)NCH;
; __device__ __forceinline__ void p3_scan_and_sb(const Params& P, float* lds) {
;     ...
;         if (wave >= 5 + SC_FREE_WAVES) {
;             constexpr unsigned NCHU = SEQ / SCH;
;             while (scw[1] < NCHU || scw[2] < NCHU || scw[3] < NCHU || scw[4] < NCHU) __builtin_amdgcn_s_sleep(32);
;         }
.LBB0_1246:
	s_waitcnt vmcnt(0)
	s_and_saveexec_b64 s[0:1], s[4:5]
	s_add_i32 s2, 0, 0x23000
	v_mov_b32_e32 v2, 0x100
	v_mov_b32_e32 v3, s2
	ds_write_b32 v3, v2
	s_or_b64 exec, exec, s[0:1]
	s_movk_i32 s0, 0x1ff
	v_cmp_lt_u32_e32 vcc, s0, v0
	s_and_saveexec_b64 s[0:1], vcc
	s_cbranch_execz .LBB0_1260
	s_branch .LBB0_1252

; __device__ __forceinline__ void p3_scan_and_sb(const Params& P, float* lds) {
;     ...
;         if (wave >= 5 + SC_FREE_WAVES) {
;             constexpr unsigned NCHU = SEQ / SCH;
;             while (scw[1] < NCHU || scw[2] < NCHU || scw[3] < NCHU || scw[4] < NCHU) __builtin_amdgcn_s_sleep(32);
;         }
.LBB0_1251:
	s_movk_i32 s0, 0x1ff
	v_cmp_lt_u32_e32 vcc, s0, v0
	s_and_saveexec_b64 s[0:1], vcc
	s_cbranch_execz .LBB0_1260
